# P6 attention: the 1+exp adds of each 32x32 score block (and the gate SiLU) as packed f32 adds, bit-identical results
# speedup vs baseline: 1.0042x; 1.0042x over previous
; __device__ __forceinline__ void attn_phase(const Ptrs& P, int gw, int NGW, int lane) {
;     ...
;             bf16x8 k3[4], v2[2][2];
;             { const int t3 = kt > 2 ? kt - 3 : 0, t2 = kt > 1 ? kt - 2 : 0;
; #pragma unroll
;               for (int ks = 0; ks < 4; ++ks) k3[ks] = kbase[(size_t)t3 * 256 + ks * 64];
; #pragma unroll
;               for (int dt = 0; dt < 2; ++dt)
; #pragma unroll
;                   for (int s = 0; s < 2; ++s) v2[dt][s] = vbase[(size_t)t2 * 256 + (dt * 2 + s) * 64]; }
;             f32x16 sa;
; #pragma unroll
;             for (int i = 0; i < 16; ++i) sa[i] = 0.f;
; #pragma unroll
;             for (int ks = 0; ks < 4; ++ks) sa = MFMA32(kf[ks], qf[ks], sa);
;             float beta[16], f[16];
;             const bool diag = (kt == qt);
; #pragma unroll
;             for (int i = 0; i < 16; ++i) { float ff = rcpf_(1.0f + ex2(sa[i])), bt = 1.0f - ff;
;                 if (diag) { const bool valid = crow(i, hh) < r; bt = valid ? bt : 0.0f; ff = valid ? ff : 1.0f; }
;                 beta[i] = bt; f[i] = ff; }
;             float gp[4], ot[4], pr[4];
; #pragma unroll
;             for (int g = 0; g < 4; ++g) { gp[g] = (f[4 * g] * f[4 * g + 1]) * (f[4 * g + 2] * f[4 * g + 3]);
;                 const auto rr = __builtin_amdgcn_permlane32_swap(__float_as_uint(gp[g]), __float_as_uint(gp[g]), false, false);
;                 ot[g] = __uint_as_float(rr[1]); pr[g] = __uint_as_float(rr[0]) * __uint_as_float(rr[1]); }
;             float suf = Pc; float att[16];
; #pragma unroll
;             for (int g = 3; g >= 0; --g) { float p = (hh == 0) ? suf * ot[g] : suf;
;                 att[4 * g + 3] = beta[4 * g + 3] * p; p *= f[4 * g + 3];
;                 att[4 * g + 2] = beta[4 * g + 2] * p; p *= f[4 * g + 2];
;                 att[4 * g + 1] = beta[4 * g + 1] * p; p *= f[4 * g + 1];
;                 att[4 * g] = beta[4 * g] * p;
;                 suf *= pr[g]; }
;             Pc = suf;
; #pragma unroll
;             for (int i = 0; i < 16; ++i) asm("" : "+v"(att[i]));
;             bf16x8 pf[2];
; #pragma unroll
;             for (int s = 0; s < 2; ++s) { v4u t; t.x = pk2(att[8 * s], att[8 * s + 1]); t.y = pk2(att[8 * s + 2], att[8 * s + 3]); t.z = pk2(att[8 * s + 4], att[8 * s + 5]); t.w = pk2(att[8 * s + 6], att[8 * s + 7]); pf[s] = __builtin_bit_cast(bf16x8, t); }
; #pragma unroll
.Lp6_unit:
	s_mov_b32 s68, s63
	v_mov_b32_e32 v229, 1.0
	v_mov_b32_e32 v252, 1.0
	v_mov_b32_e32 v253, 1.0
	s_waitcnt vmcnt(20)
	v_mfma_f32_32x32x16_bf16 v[32:47], v[64:67], v[48:51], 0
	v_mfma_f32_32x32x16_bf16 v[32:47], v[68:71], v[52:55], v[32:47]
	v_mfma_f32_32x32x16_bf16 v[32:47], v[72:75], v[56:59], v[32:47]
	v_mfma_f32_32x32x16_bf16 v[32:47], v[76:79], v[60:63], v[32:47]
	s_sub_i32 s80, s68, 3
	s_max_i32 s80, s80, 0
	s_lshl_b32 s80, s80, 12
	s_add_u32 s74, s70, s80
	s_addc_u32 s75, s71, 0
	s_add_u32 s76, s72, s80
	s_addc_u32 s77, s73, 0
	s_nop 4
	v_exp_f32_e32 v32, v32
	v_exp_f32_e32 v33, v33
	v_exp_f32_e32 v34, v34
	v_exp_f32_e32 v35, v35
	v_exp_f32_e32 v36, v36
	v_exp_f32_e32 v37, v37
	v_exp_f32_e32 v38, v38
	v_exp_f32_e32 v39, v39
	v_exp_f32_e32 v40, v40
	v_exp_f32_e32 v41, v41
	v_exp_f32_e32 v42, v42
	v_exp_f32_e32 v43, v43
	v_exp_f32_e32 v44, v44
	v_exp_f32_e32 v45, v45
	v_exp_f32_e32 v46, v46
	v_exp_f32_e32 v47, v47
	v_pk_add_f32 v[32:33], v[32:33], v[252:253] op_sel_hi:[1,0]
	v_pk_add_f32 v[34:35], v[34:35], v[252:253] op_sel_hi:[1,0]
	v_pk_add_f32 v[36:37], v[36:37], v[252:253] op_sel_hi:[1,0]
	v_pk_add_f32 v[38:39], v[38:39], v[252:253] op_sel_hi:[1,0]
	v_pk_add_f32 v[40:41], v[40:41], v[252:253] op_sel_hi:[1,0]
	v_pk_add_f32 v[42:43], v[42:43], v[252:253] op_sel_hi:[1,0]
	v_pk_add_f32 v[44:45], v[44:45], v[252:253] op_sel_hi:[1,0]
	v_pk_add_f32 v[46:47], v[46:47], v[252:253] op_sel_hi:[1,0]
	v_rcp_f32_e32 v32, v32
	v_rcp_f32_e32 v33, v33
	v_rcp_f32_e32 v34, v34
	v_rcp_f32_e32 v35, v35
	v_rcp_f32_e32 v36, v36
	v_rcp_f32_e32 v37, v37
	v_rcp_f32_e32 v38, v38
	v_rcp_f32_e32 v39, v39
	v_rcp_f32_e32 v40, v40
	v_rcp_f32_e32 v41, v41
	v_rcp_f32_e32 v42, v42
	v_rcp_f32_e32 v43, v43
	v_rcp_f32_e32 v44, v44
	v_rcp_f32_e32 v45, v45
	v_rcp_f32_e32 v46, v46
	v_rcp_f32_e32 v47, v47
	v_cndmask_b32_e64 v32, 1.0, v32, s[4:5]
	v_cndmask_b32_e64 v33, 1.0, v33, s[6:7]
	v_cndmask_b32_e64 v34, 1.0, v34, s[8:9]
	v_cndmask_b32_e64 v35, 1.0, v35, s[10:11]
	v_cndmask_b32_e64 v36, 1.0, v36, s[12:13]
	v_cndmask_b32_e64 v37, 1.0, v37, s[14:15]
	v_cndmask_b32_e64 v38, 1.0, v38, s[16:17]
	v_cndmask_b32_e64 v39, 1.0, v39, s[18:19]
	v_cndmask_b32_e64 v40, 1.0, v40, s[20:21]
	v_cndmask_b32_e64 v41, 1.0, v41, s[22:23]
	v_cndmask_b32_e64 v42, 1.0, v42, s[24:25]
	v_cndmask_b32_e64 v43, 1.0, v43, s[26:27]
	v_cndmask_b32_e64 v44, 1.0, v44, s[28:29]
	v_cndmask_b32_e64 v45, 1.0, v45, s[30:31]
	v_cndmask_b32_e64 v46, 1.0, v46, s[34:35]
	v_cndmask_b32_e64 v47, 1.0, v47, s[36:37]
	v_mul_f32_e32 v230, v32, v33
	v_mul_f32_e32 v231, v34, v35
	v_mul_f32_e32 v219, v230, v231
	v_mul_f32_e32 v230, v36, v37
	v_mul_f32_e32 v231, v38, v39
	v_mul_f32_e32 v220, v230, v231
	v_mul_f32_e32 v230, v40, v41
	v_mul_f32_e32 v231, v42, v43
	v_mul_f32_e32 v221, v230, v231
	v_mul_f32_e32 v230, v44, v45
	v_mul_f32_e32 v231, v46, v47
	v_mul_f32_e32 v222, v230, v231
	v_mov_b32_e32 v223, v219
	v_mov_b32_e32 v224, v220
	v_mov_b32_e32 v225, v221
	v_mov_b32_e32 v226, v222
	s_nop 1
	v_permlane32_swap_b32_e32 v219, v223
	v_permlane32_swap_b32_e32 v220, v224
	v_permlane32_swap_b32_e32 v221, v225
	v_permlane32_swap_b32_e32 v222, v226
	v_mul_f32_e32 v228, v229, v226
	v_cndmask_b32_e64 v228, v229, v228, s[2:3]
	v_mul_f32_e32 v230, v228, v47
	v_sub_f32_e32 v218, v228, v230
	v_mul_f32_e32 v228, v230, v46
	v_sub_f32_e32 v217, v230, v228
	v_mul_f32_e32 v230, v228, v45
	v_sub_f32_e32 v216, v228, v230
	v_mul_f32_e32 v228, v230, v44
	v_sub_f32_e32 v215, v230, v228
	v_mul_f32_e32 v227, v222, v226
	v_mul_f32_e32 v229, v229, v227
	v_mul_f32_e32 v228, v229, v225
	v_cndmask_b32_e64 v228, v229, v228, s[2:3]
	v_mul_f32_e32 v230, v228, v43
	v_sub_f32_e32 v214, v228, v230
	v_mul_f32_e32 v228, v230, v42
	v_sub_f32_e32 v213, v230, v228
	v_mul_f32_e32 v230, v228, v41
	v_sub_f32_e32 v212, v228, v230
	v_mul_f32_e32 v228, v230, v40
	v_sub_f32_e32 v211, v230, v228
	v_mul_f32_e32 v227, v221, v225
	v_mul_f32_e32 v229, v229, v227
	v_mul_f32_e32 v228, v229, v224
	v_cndmask_b32_e64 v228, v229, v228, s[2:3]
	v_mul_f32_e32 v230, v228, v39
	v_sub_f32_e32 v210, v228, v230
	v_mul_f32_e32 v228, v230, v38
	v_sub_f32_e32 v209, v230, v228
	v_mul_f32_e32 v230, v228, v37
	v_sub_f32_e32 v208, v228, v230
	v_mul_f32_e32 v228, v230, v36
	v_sub_f32_e32 v207, v230, v228
	v_mul_f32_e32 v227, v220, v224
	v_mul_f32_e32 v229, v229, v227
	v_mul_f32_e32 v228, v229, v223
	v_cndmask_b32_e64 v228, v229, v228, s[2:3]
	v_mul_f32_e32 v230, v228, v35
	v_sub_f32_e32 v206, v228, v230
	v_mul_f32_e32 v228, v230, v34
	v_sub_f32_e32 v205, v230, v228
	v_mul_f32_e32 v230, v228, v33
	v_sub_f32_e32 v204, v228, v230
	v_mul_f32_e32 v228, v230, v32
	v_sub_f32_e32 v203, v230, v228
	v_mul_f32_e32 v227, v219, v223
	v_mul_f32_e32 v229, v229, v227
	v_cvt_pk_bf16_f32 v176, v203, v204
	v_cvt_pk_bf16_f32 v177, v205, v206
	v_cvt_pk_bf16_f32 v178, v207, v208
	v_cvt_pk_bf16_f32 v179, v209, v210
	v_cvt_pk_bf16_f32 v180, v211, v212
	v_cvt_pk_bf16_f32 v181, v213, v214
	v_cvt_pk_bf16_f32 v182, v215, v216
	v_cvt_pk_bf16_f32 v183, v217, v218
	v_cmp_nge_f32_e32 vcc, 0x8000, v229
	s_waitcnt vmcnt(16)
	s_nop 0
	v_mfma_f32_32x32x16_bf16 v[0:15], v[80:83], v[176:179], 0
	v_mfma_f32_32x32x16_bf16 v[16:31], v[88:91], v[176:179], 0
	v_mfma_f32_32x32x16_bf16 v[0:15], v[84:87], v[180:183], v[0:15]
	v_mfma_f32_32x32x16_bf16 v[16:31], v[92:95], v[180:183], v[16:31]
	s_cmp_eq_u64 vcc, 0
	s_cbranch_scc1 .Lp6_epi
	s_cmp_eq_u32 s68, 0
	s_cbranch_scc1 .Lp6_epi
	s_add_i32 s68, s68, -1
	global_load_dwordx4 v[64:67], v185, s[74:75]
	global_load_dwordx4 v[68:71], v185, s[74:75] offset:1024
	global_load_dwordx4 v[72:75], v185, s[74:75] offset:2048
	global_load_dwordx4 v[76:79], v185, s[74:75] offset:3072
	global_load_dwordx4 v[80:83], v185, s[76:77]
	global_load_dwordx4 v[84:87], v185, s[76:77] offset:1024
	global_load_dwordx4 v[88:91], v185, s[76:77] offset:2048
	global_load_dwordx4 v[92:95], v185, s[76:77] offset:3072
; __device__ __forceinline__ void attn_phase(const Ptrs& P, int gw, int NGW, int lane) {
;     ...
;             bf16x8 k3[4], v2[2][2];
;             { const int t3 = kt > 2 ? kt - 3 : 0, t2 = kt > 1 ? kt - 2 : 0;
; #pragma unroll
;               for (int ks = 0; ks < 4; ++ks) k3[ks] = kbase[(size_t)t3 * 256 + ks * 64];
; #pragma unroll
;               for (int dt = 0; dt < 2; ++dt)
; #pragma unroll
;                   for (int s = 0; s < 2; ++s) v2[dt][s] = vbase[(size_t)t2 * 256 + (dt * 2 + s) * 64]; }
;             f32x16 sa;
; #pragma unroll
;             for (int i = 0; i < 16; ++i) sa[i] = 0.f;
; #pragma unroll
;             for (int ks = 0; ks < 4; ++ks) sa = MFMA32(kf[ks], qf[ks], sa);
;             float beta[16], f[16];
;             const bool diag = (kt == qt);
; #pragma unroll
;             for (int i = 0; i < 16; ++i) { float ff = rcpf_(1.0f + ex2(sa[i])), bt = 1.0f - ff;
;                 if (diag) { const bool valid = crow(i, hh) < r; bt = valid ? bt : 0.0f; ff = valid ? ff : 1.0f; }
;                 beta[i] = bt; f[i] = ff; }
;             float gp[4], ot[4], pr[4];
; #pragma unroll
;             for (int g = 0; g < 4; ++g) { gp[g] = (f[4 * g] * f[4 * g + 1]) * (f[4 * g + 2] * f[4 * g + 3]);
;                 const auto rr = __builtin_amdgcn_permlane32_swap(__float_as_uint(gp[g]), __float_as_uint(gp[g]), false, false);
;                 ot[g] = __uint_as_float(rr[1]); pr[g] = __uint_as_float(rr[0]) * __uint_as_float(rr[1]); }
;             float suf = Pc; float att[16];
; #pragma unroll
;             for (int g = 3; g >= 0; --g) { float p = (hh == 0) ? suf * ot[g] : suf;
;                 att[4 * g + 3] = beta[4 * g + 3] * p; p *= f[4 * g + 3];
;                 att[4 * g + 2] = beta[4 * g + 2] * p; p *= f[4 * g + 2];
;                 att[4 * g + 1] = beta[4 * g + 1] * p; p *= f[4 * g + 1];
;                 att[4 * g] = beta[4 * g] * p;
;                 suf *= pr[g]; }
;             Pc = suf;
; #pragma unroll
;             for (int i = 0; i < 16; ++i) asm("" : "+v"(att[i]));
;             bf16x8 pf[2];
; #pragma unroll
;             for (int s = 0; s < 2; ++s) { v4u t; t.x = pk2(att[8 * s], att[8 * s + 1]); t.y = pk2(att[8 * s + 2], att[8 * s + 3]); t.z = pk2(att[8 * s + 4], att[8 * s + 5]); t.w = pk2(att[8 * s + 6], att[8 * s + 7]); pf[s] = __builtin_bit_cast(bf16x8, t); }
; #pragma unroll
.Lp6_loop:
	s_waitcnt vmcnt(20)
	v_mfma_f32_32x32x16_bf16 v[32:47], v[96:99], v[48:51], 0
	v_mfma_f32_32x32x16_bf16 v[32:47], v[100:103], v[52:55], v[32:47]
	v_mfma_f32_32x32x16_bf16 v[32:47], v[104:107], v[56:59], v[32:47]
	v_mfma_f32_32x32x16_bf16 v[32:47], v[108:111], v[60:63], v[32:47]
	s_sub_i32 s80, s68, 3
	s_max_i32 s80, s80, 0
	s_lshl_b32 s80, s80, 12
	s_add_u32 s74, s70, s80
	s_addc_u32 s75, s71, 0
	s_add_u32 s76, s72, s80
	s_addc_u32 s77, s73, 0
	s_nop 4
	v_exp_f32_e32 v32, v32
	v_exp_f32_e32 v33, v33
	v_exp_f32_e32 v34, v34
	v_exp_f32_e32 v35, v35
	v_exp_f32_e32 v36, v36
	v_exp_f32_e32 v37, v37
	v_exp_f32_e32 v38, v38
	v_exp_f32_e32 v39, v39
	v_exp_f32_e32 v40, v40
	v_exp_f32_e32 v41, v41
	v_exp_f32_e32 v42, v42
	v_exp_f32_e32 v43, v43
	v_exp_f32_e32 v44, v44
	v_exp_f32_e32 v45, v45
	v_exp_f32_e32 v46, v46
	v_exp_f32_e32 v47, v47
	v_pk_add_f32 v[32:33], v[32:33], v[252:253] op_sel_hi:[1,0]
	v_pk_add_f32 v[34:35], v[34:35], v[252:253] op_sel_hi:[1,0]
	v_pk_add_f32 v[36:37], v[36:37], v[252:253] op_sel_hi:[1,0]
	v_pk_add_f32 v[38:39], v[38:39], v[252:253] op_sel_hi:[1,0]
	v_pk_add_f32 v[40:41], v[40:41], v[252:253] op_sel_hi:[1,0]
	v_pk_add_f32 v[42:43], v[42:43], v[252:253] op_sel_hi:[1,0]
	v_pk_add_f32 v[44:45], v[44:45], v[252:253] op_sel_hi:[1,0]
	v_pk_add_f32 v[46:47], v[46:47], v[252:253] op_sel_hi:[1,0]
	v_rcp_f32_e32 v32, v32
	v_rcp_f32_e32 v33, v33
	v_rcp_f32_e32 v34, v34
	v_rcp_f32_e32 v35, v35
	v_rcp_f32_e32 v36, v36
	v_rcp_f32_e32 v37, v37
	v_rcp_f32_e32 v38, v38
	v_rcp_f32_e32 v39, v39
	v_rcp_f32_e32 v40, v40
	v_rcp_f32_e32 v41, v41
	v_rcp_f32_e32 v42, v42
	v_rcp_f32_e32 v43, v43
	v_rcp_f32_e32 v44, v44
	v_rcp_f32_e32 v45, v45
	v_rcp_f32_e32 v46, v46
	v_rcp_f32_e32 v47, v47
	v_mul_f32_e32 v230, v32, v33
	v_mul_f32_e32 v231, v34, v35
	v_mul_f32_e32 v219, v230, v231
	v_mul_f32_e32 v230, v36, v37
	v_mul_f32_e32 v231, v38, v39
	v_mul_f32_e32 v220, v230, v231
	v_mul_f32_e32 v230, v40, v41
	v_mul_f32_e32 v231, v42, v43
	v_mul_f32_e32 v221, v230, v231
	v_mul_f32_e32 v230, v44, v45
	v_mul_f32_e32 v231, v46, v47
	v_mul_f32_e32 v222, v230, v231
	v_mov_b32_e32 v223, v219
	v_mov_b32_e32 v224, v220
	v_mov_b32_e32 v225, v221
	v_mov_b32_e32 v226, v222
	s_nop 1
	v_permlane32_swap_b32_e32 v219, v223
	v_permlane32_swap_b32_e32 v220, v224
	v_permlane32_swap_b32_e32 v221, v225
	v_permlane32_swap_b32_e32 v222, v226
	v_mul_f32_e32 v228, v229, v226
	v_cndmask_b32_e64 v228, v229, v228, s[2:3]
	v_mul_f32_e32 v230, v228, v47
	v_sub_f32_e32 v218, v228, v230
	v_mul_f32_e32 v228, v230, v46
	v_sub_f32_e32 v217, v230, v228
	v_mul_f32_e32 v230, v228, v45
	v_sub_f32_e32 v216, v228, v230
	v_mul_f32_e32 v228, v230, v44
	v_sub_f32_e32 v215, v230, v228
	v_mul_f32_e32 v227, v222, v226
	v_mul_f32_e32 v229, v229, v227
	v_mul_f32_e32 v228, v229, v225
	v_cndmask_b32_e64 v228, v229, v228, s[2:3]
	v_mul_f32_e32 v230, v228, v43
	v_sub_f32_e32 v214, v228, v230
	v_mul_f32_e32 v228, v230, v42
	v_sub_f32_e32 v213, v230, v228
	v_mul_f32_e32 v230, v228, v41
	v_sub_f32_e32 v212, v228, v230
	v_mul_f32_e32 v228, v230, v40
	v_sub_f32_e32 v211, v230, v228
	v_mul_f32_e32 v227, v221, v225
	v_mul_f32_e32 v229, v229, v227
	v_mul_f32_e32 v228, v229, v224
	v_cndmask_b32_e64 v228, v229, v228, s[2:3]
	v_mul_f32_e32 v230, v228, v39
	v_sub_f32_e32 v210, v228, v230
	v_mul_f32_e32 v228, v230, v38
	v_sub_f32_e32 v209, v230, v228
	v_mul_f32_e32 v230, v228, v37
	v_sub_f32_e32 v208, v228, v230
	v_mul_f32_e32 v228, v230, v36
	v_sub_f32_e32 v207, v230, v228
	v_mul_f32_e32 v227, v220, v224
	v_mul_f32_e32 v229, v229, v227
	v_mul_f32_e32 v228, v229, v223
	v_cndmask_b32_e64 v228, v229, v228, s[2:3]
	v_mul_f32_e32 v230, v228, v35
	v_sub_f32_e32 v206, v228, v230
	v_mul_f32_e32 v228, v230, v34
	v_sub_f32_e32 v205, v230, v228
	v_mul_f32_e32 v230, v228, v33
	v_sub_f32_e32 v204, v228, v230
	v_mul_f32_e32 v228, v230, v32
	v_sub_f32_e32 v203, v230, v228
	v_mul_f32_e32 v227, v219, v223
	v_mul_f32_e32 v229, v229, v227
	v_cvt_pk_bf16_f32 v176, v203, v204
	v_cvt_pk_bf16_f32 v177, v205, v206
	v_cvt_pk_bf16_f32 v178, v207, v208
	v_cvt_pk_bf16_f32 v179, v209, v210
	v_cvt_pk_bf16_f32 v180, v211, v212
	v_cvt_pk_bf16_f32 v181, v213, v214
	v_cvt_pk_bf16_f32 v182, v215, v216
	v_cvt_pk_bf16_f32 v183, v217, v218
	v_cmp_nge_f32_e32 vcc, 0x8000, v229
	s_waitcnt vmcnt(16)
	s_nop 0
	v_mfma_f32_32x32x16_bf16 v[0:15], v[112:115], v[176:179], v[0:15]
	v_mfma_f32_32x32x16_bf16 v[16:31], v[120:123], v[176:179], v[16:31]
	v_mfma_f32_32x32x16_bf16 v[0:15], v[116:119], v[180:183], v[0:15]
	v_mfma_f32_32x32x16_bf16 v[16:31], v[124:127], v[180:183], v[16:31]
	s_cmp_eq_u64 vcc, 0
	s_cbranch_scc1 .Lp6_epi
	s_cmp_eq_u32 s68, 0
	s_cbranch_scc1 .Lp6_epi
; __device__ __forceinline__ void attn_phase(const Ptrs& P, int gw, int NGW, int lane) {
;     ...
;             bf16x8 k3[4], v2[2][2];
;             { const int t3 = kt > 2 ? kt - 3 : 0, t2 = kt > 1 ? kt - 2 : 0;
; #pragma unroll
;               for (int ks = 0; ks < 4; ++ks) k3[ks] = kbase[(size_t)t3 * 256 + ks * 64];
; #pragma unroll
;               for (int dt = 0; dt < 2; ++dt)
; #pragma unroll
;                   for (int s = 0; s < 2; ++s) v2[dt][s] = vbase[(size_t)t2 * 256 + (dt * 2 + s) * 64]; }
;             f32x16 sa;
; #pragma unroll
;             for (int i = 0; i < 16; ++i) sa[i] = 0.f;
; #pragma unroll
;             for (int ks = 0; ks < 4; ++ks) sa = MFMA32(kf[ks], qf[ks], sa);
;             float beta[16], f[16];
;             const bool diag = (kt == qt);
; #pragma unroll
;             for (int i = 0; i < 16; ++i) { float ff = rcpf_(1.0f + ex2(sa[i])), bt = 1.0f - ff;
;                 if (diag) { const bool valid = crow(i, hh) < r; bt = valid ? bt : 0.0f; ff = valid ? ff : 1.0f; }
;                 beta[i] = bt; f[i] = ff; }
;             float gp[4], ot[4], pr[4];
; #pragma unroll
;             for (int g = 0; g < 4; ++g) { gp[g] = (f[4 * g] * f[4 * g + 1]) * (f[4 * g + 2] * f[4 * g + 3]);
;                 const auto rr = __builtin_amdgcn_permlane32_swap(__float_as_uint(gp[g]), __float_as_uint(gp[g]), false, false);
;                 ot[g] = __uint_as_float(rr[1]); pr[g] = __uint_as_float(rr[0]) * __uint_as_float(rr[1]); }
;             float suf = Pc; float att[16];
; #pragma unroll
;             for (int g = 3; g >= 0; --g) { float p = (hh == 0) ? suf * ot[g] : suf;
;                 att[4 * g + 3] = beta[4 * g + 3] * p; p *= f[4 * g + 3];
;                 att[4 * g + 2] = beta[4 * g + 2] * p; p *= f[4 * g + 2];
;                 att[4 * g + 1] = beta[4 * g + 1] * p; p *= f[4 * g + 1];
;                 att[4 * g] = beta[4 * g] * p;
;                 suf *= pr[g]; }
;             Pc = suf;
; #pragma unroll
;             for (int i = 0; i < 16; ++i) asm("" : "+v"(att[i]));
;             bf16x8 pf[2];
; #pragma unroll
;             for (int s = 0; s < 2; ++s) { v4u t; t.x = pk2(att[8 * s], att[8 * s + 1]); t.y = pk2(att[8 * s + 2], att[8 * s + 3]); t.z = pk2(att[8 * s + 4], att[8 * s + 5]); t.w = pk2(att[8 * s + 6], att[8 * s + 7]); pf[s] = __builtin_bit_cast(bf16x8, t); }
; #pragma unroll
	s_add_i32 s68, s68, -1
	global_load_dwordx4 v[96:99], v185, s[74:75]
	global_load_dwordx4 v[100:103], v185, s[74:75] offset:1024
	global_load_dwordx4 v[104:107], v185, s[74:75] offset:2048
	global_load_dwordx4 v[108:111], v185, s[74:75] offset:3072
	global_load_dwordx4 v[112:115], v185, s[76:77]
	global_load_dwordx4 v[116:119], v185, s[76:77] offset:1024
	global_load_dwordx4 v[120:123], v185, s[76:77] offset:2048
	global_load_dwordx4 v[124:127], v185, s[76:77] offset:3072
	s_waitcnt vmcnt(20)
	v_mfma_f32_32x32x16_bf16 v[32:47], v[128:131], v[48:51], 0
	v_mfma_f32_32x32x16_bf16 v[32:47], v[132:135], v[52:55], v[32:47]
	v_mfma_f32_32x32x16_bf16 v[32:47], v[136:139], v[56:59], v[32:47]
	v_mfma_f32_32x32x16_bf16 v[32:47], v[140:143], v[60:63], v[32:47]
	s_sub_i32 s80, s68, 3
	s_max_i32 s80, s80, 0
	s_lshl_b32 s80, s80, 12
	s_add_u32 s74, s70, s80
	s_addc_u32 s75, s71, 0
	s_add_u32 s76, s72, s80
	s_addc_u32 s77, s73, 0
	s_nop 4
	v_exp_f32_e32 v32, v32
	v_exp_f32_e32 v33, v33
	v_exp_f32_e32 v34, v34
	v_exp_f32_e32 v35, v35
	v_exp_f32_e32 v36, v36
	v_exp_f32_e32 v37, v37
	v_exp_f32_e32 v38, v38
	v_exp_f32_e32 v39, v39
	v_exp_f32_e32 v40, v40
	v_exp_f32_e32 v41, v41
	v_exp_f32_e32 v42, v42
	v_exp_f32_e32 v43, v43
	v_exp_f32_e32 v44, v44
	v_exp_f32_e32 v45, v45
	v_exp_f32_e32 v46, v46
	v_exp_f32_e32 v47, v47
	v_pk_add_f32 v[32:33], v[32:33], v[252:253] op_sel_hi:[1,0]
	v_pk_add_f32 v[34:35], v[34:35], v[252:253] op_sel_hi:[1,0]
	v_pk_add_f32 v[36:37], v[36:37], v[252:253] op_sel_hi:[1,0]
	v_pk_add_f32 v[38:39], v[38:39], v[252:253] op_sel_hi:[1,0]
	v_pk_add_f32 v[40:41], v[40:41], v[252:253] op_sel_hi:[1,0]
	v_pk_add_f32 v[42:43], v[42:43], v[252:253] op_sel_hi:[1,0]
	v_pk_add_f32 v[44:45], v[44:45], v[252:253] op_sel_hi:[1,0]
	v_pk_add_f32 v[46:47], v[46:47], v[252:253] op_sel_hi:[1,0]
	v_rcp_f32_e32 v32, v32
	v_rcp_f32_e32 v33, v33
	v_rcp_f32_e32 v34, v34
	v_rcp_f32_e32 v35, v35
	v_rcp_f32_e32 v36, v36
	v_rcp_f32_e32 v37, v37
	v_rcp_f32_e32 v38, v38
	v_rcp_f32_e32 v39, v39
	v_rcp_f32_e32 v40, v40
	v_rcp_f32_e32 v41, v41
	v_rcp_f32_e32 v42, v42
	v_rcp_f32_e32 v43, v43
	v_rcp_f32_e32 v44, v44
	v_rcp_f32_e32 v45, v45
	v_rcp_f32_e32 v46, v46
	v_rcp_f32_e32 v47, v47
	v_mul_f32_e32 v230, v32, v33
	v_mul_f32_e32 v231, v34, v35
	v_mul_f32_e32 v219, v230, v231
	v_mul_f32_e32 v230, v36, v37
	v_mul_f32_e32 v231, v38, v39
	v_mul_f32_e32 v220, v230, v231
	v_mul_f32_e32 v230, v40, v41
	v_mul_f32_e32 v231, v42, v43
	v_mul_f32_e32 v221, v230, v231
	v_mul_f32_e32 v230, v44, v45
	v_mul_f32_e32 v231, v46, v47
	v_mul_f32_e32 v222, v230, v231
	v_mov_b32_e32 v223, v219
	v_mov_b32_e32 v224, v220
	v_mov_b32_e32 v225, v221
	v_mov_b32_e32 v226, v222
	s_nop 1
	v_permlane32_swap_b32_e32 v219, v223
	v_permlane32_swap_b32_e32 v220, v224
	v_permlane32_swap_b32_e32 v221, v225
	v_permlane32_swap_b32_e32 v222, v226
	v_mul_f32_e32 v228, v229, v226
	v_cndmask_b32_e64 v228, v229, v228, s[2:3]
	v_mul_f32_e32 v230, v228, v47
	v_sub_f32_e32 v218, v228, v230
	v_mul_f32_e32 v228, v230, v46
	v_sub_f32_e32 v217, v230, v228
	v_mul_f32_e32 v230, v228, v45
	v_sub_f32_e32 v216, v228, v230
	v_mul_f32_e32 v228, v230, v44
	v_sub_f32_e32 v215, v230, v228
	v_mul_f32_e32 v227, v222, v226
	v_mul_f32_e32 v229, v229, v227
	v_mul_f32_e32 v228, v229, v225
	v_cndmask_b32_e64 v228, v229, v228, s[2:3]
	v_mul_f32_e32 v230, v228, v43
	v_sub_f32_e32 v214, v228, v230
	v_mul_f32_e32 v228, v230, v42
	v_sub_f32_e32 v213, v230, v228
	v_mul_f32_e32 v230, v228, v41
	v_sub_f32_e32 v212, v228, v230
	v_mul_f32_e32 v228, v230, v40
	v_sub_f32_e32 v211, v230, v228
	v_mul_f32_e32 v227, v221, v225
	v_mul_f32_e32 v229, v229, v227
	v_mul_f32_e32 v228, v229, v224
	v_cndmask_b32_e64 v228, v229, v228, s[2:3]
	v_mul_f32_e32 v230, v228, v39
	v_sub_f32_e32 v210, v228, v230
	v_mul_f32_e32 v228, v230, v38
	v_sub_f32_e32 v209, v230, v228
	v_mul_f32_e32 v230, v228, v37
	v_sub_f32_e32 v208, v228, v230
	v_mul_f32_e32 v228, v230, v36
	v_sub_f32_e32 v207, v230, v228
	v_mul_f32_e32 v227, v220, v224
	v_mul_f32_e32 v229, v229, v227
	v_mul_f32_e32 v228, v229, v223
	v_cndmask_b32_e64 v228, v229, v228, s[2:3]
	v_mul_f32_e32 v230, v228, v35
	v_sub_f32_e32 v206, v228, v230
	v_mul_f32_e32 v228, v230, v34
	v_sub_f32_e32 v205, v230, v228
	v_mul_f32_e32 v230, v228, v33
	v_sub_f32_e32 v204, v228, v230
	v_mul_f32_e32 v228, v230, v32
	v_sub_f32_e32 v203, v230, v228
	v_mul_f32_e32 v227, v219, v223
	v_mul_f32_e32 v229, v229, v227
	v_cvt_pk_bf16_f32 v176, v203, v204
	v_cvt_pk_bf16_f32 v177, v205, v206
	v_cvt_pk_bf16_f32 v178, v207, v208
	v_cvt_pk_bf16_f32 v179, v209, v210
	v_cvt_pk_bf16_f32 v180, v211, v212
	v_cvt_pk_bf16_f32 v181, v213, v214
	v_cvt_pk_bf16_f32 v182, v215, v216
	v_cvt_pk_bf16_f32 v183, v217, v218
	v_cmp_nge_f32_e32 vcc, 0x8000, v229
	s_waitcnt vmcnt(16)
	s_nop 0
	v_mfma_f32_32x32x16_bf16 v[0:15], v[144:147], v[176:179], v[0:15]
	v_mfma_f32_32x32x16_bf16 v[16:31], v[152:155], v[176:179], v[16:31]
	v_mfma_f32_32x32x16_bf16 v[0:15], v[148:151], v[180:183], v[0:15]
	v_mfma_f32_32x32x16_bf16 v[16:31], v[156:159], v[180:183], v[16:31]
	s_cmp_eq_u64 vcc, 0
	s_cbranch_scc1 .Lp6_epi
	s_cmp_eq_u32 s68, 0
	s_cbranch_scc1 .Lp6_epi
; __device__ __forceinline__ void attn_phase(const Ptrs& P, int gw, int NGW, int lane) {
;     ...
;             bf16x8 k3[4], v2[2][2];
;             { const int t3 = kt > 2 ? kt - 3 : 0, t2 = kt > 1 ? kt - 2 : 0;
; #pragma unroll
;               for (int ks = 0; ks < 4; ++ks) k3[ks] = kbase[(size_t)t3 * 256 + ks * 64];
; #pragma unroll
;               for (int dt = 0; dt < 2; ++dt)
; #pragma unroll
;                   for (int s = 0; s < 2; ++s) v2[dt][s] = vbase[(size_t)t2 * 256 + (dt * 2 + s) * 64]; }
;             f32x16 sa;
; #pragma unroll
;             for (int i = 0; i < 16; ++i) sa[i] = 0.f;
; #pragma unroll
;             for (int ks = 0; ks < 4; ++ks) sa = MFMA32(kf[ks], qf[ks], sa);
;             float beta[16], f[16];
;             const bool diag = (kt == qt);
; #pragma unroll
;             for (int i = 0; i < 16; ++i) { float ff = rcpf_(1.0f + ex2(sa[i])), bt = 1.0f - ff;
;                 if (diag) { const bool valid = crow(i, hh) < r; bt = valid ? bt : 0.0f; ff = valid ? ff : 1.0f; }
;                 beta[i] = bt; f[i] = ff; }
;             float gp[4], ot[4], pr[4];
; #pragma unroll
;             for (int g = 0; g < 4; ++g) { gp[g] = (f[4 * g] * f[4 * g + 1]) * (f[4 * g + 2] * f[4 * g + 3]);
;                 const auto rr = __builtin_amdgcn_permlane32_swap(__float_as_uint(gp[g]), __float_as_uint(gp[g]), false, false);
;                 ot[g] = __uint_as_float(rr[1]); pr[g] = __uint_as_float(rr[0]) * __uint_as_float(rr[1]); }
;             float suf = Pc; float att[16];
; #pragma unroll
;             for (int g = 3; g >= 0; --g) { float p = (hh == 0) ? suf * ot[g] : suf;
;                 att[4 * g + 3] = beta[4 * g + 3] * p; p *= f[4 * g + 3];
;                 att[4 * g + 2] = beta[4 * g + 2] * p; p *= f[4 * g + 2];
;                 att[4 * g + 1] = beta[4 * g + 1] * p; p *= f[4 * g + 1];
;                 att[4 * g] = beta[4 * g] * p;
;                 suf *= pr[g]; }
;             Pc = suf;
; #pragma unroll
;             for (int i = 0; i < 16; ++i) asm("" : "+v"(att[i]));
;             bf16x8 pf[2];
; #pragma unroll
;             for (int s = 0; s < 2; ++s) { v4u t; t.x = pk2(att[8 * s], att[8 * s + 1]); t.y = pk2(att[8 * s + 2], att[8 * s + 3]); t.z = pk2(att[8 * s + 4], att[8 * s + 5]); t.w = pk2(att[8 * s + 6], att[8 * s + 7]); pf[s] = __builtin_bit_cast(bf16x8, t); }
; #pragma unroll
	s_add_i32 s68, s68, -1
	global_load_dwordx4 v[128:131], v185, s[74:75]
	global_load_dwordx4 v[132:135], v185, s[74:75] offset:1024
	global_load_dwordx4 v[136:139], v185, s[74:75] offset:2048
	global_load_dwordx4 v[140:143], v185, s[74:75] offset:3072
	global_load_dwordx4 v[144:147], v185, s[76:77]
	global_load_dwordx4 v[148:151], v185, s[76:77] offset:1024
	global_load_dwordx4 v[152:155], v185, s[76:77] offset:2048
	global_load_dwordx4 v[156:159], v185, s[76:77] offset:3072
	s_waitcnt vmcnt(20)
	v_mfma_f32_32x32x16_bf16 v[32:47], v[64:67], v[48:51], 0
	v_mfma_f32_32x32x16_bf16 v[32:47], v[68:71], v[52:55], v[32:47]
	v_mfma_f32_32x32x16_bf16 v[32:47], v[72:75], v[56:59], v[32:47]
	v_mfma_f32_32x32x16_bf16 v[32:47], v[76:79], v[60:63], v[32:47]
	s_sub_i32 s80, s68, 3
	s_max_i32 s80, s80, 0
	s_lshl_b32 s80, s80, 12
	s_add_u32 s74, s70, s80
	s_addc_u32 s75, s71, 0
	s_add_u32 s76, s72, s80
	s_addc_u32 s77, s73, 0
	s_nop 4
	v_exp_f32_e32 v32, v32
	v_exp_f32_e32 v33, v33
	v_exp_f32_e32 v34, v34
	v_exp_f32_e32 v35, v35
	v_exp_f32_e32 v36, v36
	v_exp_f32_e32 v37, v37
	v_exp_f32_e32 v38, v38
	v_exp_f32_e32 v39, v39
	v_exp_f32_e32 v40, v40
	v_exp_f32_e32 v41, v41
	v_exp_f32_e32 v42, v42
	v_exp_f32_e32 v43, v43
	v_exp_f32_e32 v44, v44
	v_exp_f32_e32 v45, v45
	v_exp_f32_e32 v46, v46
	v_exp_f32_e32 v47, v47
	v_pk_add_f32 v[32:33], v[32:33], v[252:253] op_sel_hi:[1,0]
	v_pk_add_f32 v[34:35], v[34:35], v[252:253] op_sel_hi:[1,0]
	v_pk_add_f32 v[36:37], v[36:37], v[252:253] op_sel_hi:[1,0]
	v_pk_add_f32 v[38:39], v[38:39], v[252:253] op_sel_hi:[1,0]
	v_pk_add_f32 v[40:41], v[40:41], v[252:253] op_sel_hi:[1,0]
	v_pk_add_f32 v[42:43], v[42:43], v[252:253] op_sel_hi:[1,0]
	v_pk_add_f32 v[44:45], v[44:45], v[252:253] op_sel_hi:[1,0]
	v_pk_add_f32 v[46:47], v[46:47], v[252:253] op_sel_hi:[1,0]
	v_rcp_f32_e32 v32, v32
	v_rcp_f32_e32 v33, v33
	v_rcp_f32_e32 v34, v34
	v_rcp_f32_e32 v35, v35
	v_rcp_f32_e32 v36, v36
	v_rcp_f32_e32 v37, v37
	v_rcp_f32_e32 v38, v38
	v_rcp_f32_e32 v39, v39
	v_rcp_f32_e32 v40, v40
	v_rcp_f32_e32 v41, v41
	v_rcp_f32_e32 v42, v42
	v_rcp_f32_e32 v43, v43
	v_rcp_f32_e32 v44, v44
	v_rcp_f32_e32 v45, v45
	v_rcp_f32_e32 v46, v46
	v_rcp_f32_e32 v47, v47
	v_mul_f32_e32 v230, v32, v33
	v_mul_f32_e32 v231, v34, v35
	v_mul_f32_e32 v219, v230, v231
	v_mul_f32_e32 v230, v36, v37
	v_mul_f32_e32 v231, v38, v39
	v_mul_f32_e32 v220, v230, v231
	v_mul_f32_e32 v230, v40, v41
	v_mul_f32_e32 v231, v42, v43
	v_mul_f32_e32 v221, v230, v231
	v_mul_f32_e32 v230, v44, v45
	v_mul_f32_e32 v231, v46, v47
	v_mul_f32_e32 v222, v230, v231
	v_mov_b32_e32 v223, v219
	v_mov_b32_e32 v224, v220
	v_mov_b32_e32 v225, v221
	v_mov_b32_e32 v226, v222
	s_nop 1
	v_permlane32_swap_b32_e32 v219, v223
	v_permlane32_swap_b32_e32 v220, v224
	v_permlane32_swap_b32_e32 v221, v225
	v_permlane32_swap_b32_e32 v222, v226
	v_mul_f32_e32 v228, v229, v226
	v_cndmask_b32_e64 v228, v229, v228, s[2:3]
	v_mul_f32_e32 v230, v228, v47
	v_sub_f32_e32 v218, v228, v230
	v_mul_f32_e32 v228, v230, v46
	v_sub_f32_e32 v217, v230, v228
	v_mul_f32_e32 v230, v228, v45
	v_sub_f32_e32 v216, v228, v230
	v_mul_f32_e32 v228, v230, v44
	v_sub_f32_e32 v215, v230, v228
	v_mul_f32_e32 v227, v222, v226
	v_mul_f32_e32 v229, v229, v227
	v_mul_f32_e32 v228, v229, v225
	v_cndmask_b32_e64 v228, v229, v228, s[2:3]
	v_mul_f32_e32 v230, v228, v43
	v_sub_f32_e32 v214, v228, v230
	v_mul_f32_e32 v228, v230, v42
	v_sub_f32_e32 v213, v230, v228
	v_mul_f32_e32 v230, v228, v41
	v_sub_f32_e32 v212, v228, v230
	v_mul_f32_e32 v228, v230, v40
	v_sub_f32_e32 v211, v230, v228
	v_mul_f32_e32 v227, v221, v225
	v_mul_f32_e32 v229, v229, v227
	v_mul_f32_e32 v228, v229, v224
	v_cndmask_b32_e64 v228, v229, v228, s[2:3]
	v_mul_f32_e32 v230, v228, v39
	v_sub_f32_e32 v210, v228, v230
	v_mul_f32_e32 v228, v230, v38
	v_sub_f32_e32 v209, v230, v228
	v_mul_f32_e32 v230, v228, v37
	v_sub_f32_e32 v208, v228, v230
	v_mul_f32_e32 v228, v230, v36
	v_sub_f32_e32 v207, v230, v228
	v_mul_f32_e32 v227, v220, v224
	v_mul_f32_e32 v229, v229, v227
	v_mul_f32_e32 v228, v229, v223
	v_cndmask_b32_e64 v228, v229, v228, s[2:3]
	v_mul_f32_e32 v230, v228, v35
	v_sub_f32_e32 v206, v228, v230
	v_mul_f32_e32 v228, v230, v34
	v_sub_f32_e32 v205, v230, v228
	v_mul_f32_e32 v230, v228, v33
	v_sub_f32_e32 v204, v228, v230
	v_mul_f32_e32 v228, v230, v32
	v_sub_f32_e32 v203, v230, v228
	v_mul_f32_e32 v227, v219, v223
	v_mul_f32_e32 v229, v229, v227
	v_cvt_pk_bf16_f32 v176, v203, v204
	v_cvt_pk_bf16_f32 v177, v205, v206
	v_cvt_pk_bf16_f32 v178, v207, v208
	v_cvt_pk_bf16_f32 v179, v209, v210
	v_cvt_pk_bf16_f32 v180, v211, v212
	v_cvt_pk_bf16_f32 v181, v213, v214
	v_cvt_pk_bf16_f32 v182, v215, v216
	v_cvt_pk_bf16_f32 v183, v217, v218
	v_cmp_nge_f32_e32 vcc, 0x8000, v229
	s_waitcnt vmcnt(16)
	s_nop 0
	v_mfma_f32_32x32x16_bf16 v[0:15], v[80:83], v[176:179], v[0:15]
	v_mfma_f32_32x32x16_bf16 v[16:31], v[88:91], v[176:179], v[16:31]
	v_mfma_f32_32x32x16_bf16 v[0:15], v[84:87], v[180:183], v[0:15]
	v_mfma_f32_32x32x16_bf16 v[16:31], v[92:95], v[180:183], v[16:31]
	s_cmp_eq_u64 vcc, 0
	s_cbranch_scc1 .Lp6_epi
	s_cmp_eq_u32 s68, 0
	s_cbranch_scc1 .Lp6_epi
	s_add_i32 s68, s68, -1
	global_load_dwordx4 v[64:67], v185, s[74:75]
	global_load_dwordx4 v[68:71], v185, s[74:75] offset:1024
	global_load_dwordx4 v[72:75], v185, s[74:75] offset:2048
	global_load_dwordx4 v[76:79], v185, s[74:75] offset:3072
	global_load_dwordx4 v[80:83], v185, s[76:77]
	global_load_dwordx4 v[84:87], v185, s[76:77] offset:1024
	global_load_dwordx4 v[88:91], v185, s[76:77] offset:2048
	global_load_dwordx4 v[92:95], v185, s[76:77] offset:3072
	s_branch .Lp6_loop

; __device__ __forceinline__ unsigned pk2(float lo, float hi) { f32x2_t v = {lo, hi}; bf16x2_t b = __builtin_convertvector(v, bf16x2_t); return __builtin_bit_cast(unsigned, b); }
; __device__ __forceinline__ float bflo(unsigned u) { return __uint_as_float(u << 16); }
; __device__ __forceinline__ float bfhi(unsigned u) { return __uint_as_float(u & 0xffff0000u); }
; __device__ __forceinline__ float sigmoid_(float x) { return rcpf_(1.0f + ex2(-LOG2E * x)); }
; __device__ __forceinline__ void attn_phase(const Ptrs& P, int gw, int NGW, int lane) {
;     ...
;         const size_t row = rowbase + qt * 32 + r;
;         bf16* op = OG + row * AW + h * HD + 8 * hh;
; #pragma unroll
;         for (int dt = 0; dt < 2; ++dt)
; #pragma unroll
;             for (int g = 0; g < 4; g += 2) { v2u pk[2];
; #pragma unroll
;                 for (int e = 0; e < 2; ++e) { const v2u graw = gq_[dt * 4 + g + e]; const int i0 = 4 * (g + e);
;                     const float g0 = bflo(graw.x), g1 = bfhi(graw.x), g2 = bflo(graw.y), g3 = bfhi(graw.y);
;                     const float v0 = dt ? o1[i0] : o0[i0], v1 = dt ? o1[i0 + 1] : o0[i0 + 1], v2 = dt ? o1[i0 + 2] : o0[i0 + 2], v3 = dt ? o1[i0 + 3] : o0[i0 + 3];
;                     float w0 = v0 * (g0 * sigmoid_(g0)), w1 = v1 * (g1 * sigmoid_(g1)), w2 = v2 * (g2 * sigmoid_(g2)), w3 = v3 * (g3 * sigmoid_(g3));
;                     asm("" : "+v"(w0)); asm("" : "+v"(w1)); asm("" : "+v"(w2)); asm("" : "+v"(w3));
;                     pk[e].x = pk2(w0, w1); pk[e].y = pk2(w2, w3); }
;                 const auto rx = __builtin_amdgcn_permlane32_swap(pk[0].x, pk[1].x, false, false), ry = __builtin_amdgcn_permlane32_swap(pk[0].y, pk[1].y, false, false);
;                 const v4u o = {rx[0], ry[0], rx[1], ry[1]};
;                 *(v4u*)(op + dt * 32 + 8 * g) = o; }
.Lp6_epi_compute:
	v_lshlrev_b32_e32 v240, 16, v187
	v_and_b32_e32 v241, 0xffff0000, v187
	v_lshlrev_b32_e32 v242, 16, v188
	v_and_b32_e32 v243, 0xffff0000, v188
	v_mul_f32_e32 v244, 0xbfb8aa3b, v240
	v_mul_f32_e32 v245, 0xbfb8aa3b, v241
	v_mul_f32_e32 v246, 0xbfb8aa3b, v242
	v_mul_f32_e32 v247, 0xbfb8aa3b, v243
	v_exp_f32_e32 v244, v244
	v_exp_f32_e32 v245, v245
	v_exp_f32_e32 v246, v246
	v_exp_f32_e32 v247, v247
	v_pk_add_f32 v[244:245], v[244:245], v[252:253] op_sel_hi:[1,0]
	v_pk_add_f32 v[246:247], v[246:247], v[252:253] op_sel_hi:[1,0]
	v_rcp_f32_e32 v244, v244
	v_rcp_f32_e32 v245, v245
	v_rcp_f32_e32 v246, v246
	v_rcp_f32_e32 v247, v247
	v_mul_f32_e32 v240, v244, v240
	v_mul_f32_e32 v241, v245, v241
	v_mul_f32_e32 v242, v246, v242
	v_mul_f32_e32 v243, v247, v243
	v_mul_f32_e32 v240, v240, v0
	v_mul_f32_e32 v241, v241, v1
	v_mul_f32_e32 v242, v242, v2
	v_mul_f32_e32 v243, v243, v3
	v_cvt_pk_bf16_f32 v248, v240, v241
	v_cvt_pk_bf16_f32 v249, v242, v243
	v_lshlrev_b32_e32 v240, 16, v189
	v_and_b32_e32 v241, 0xffff0000, v189
	v_lshlrev_b32_e32 v242, 16, v190
	v_and_b32_e32 v243, 0xffff0000, v190
	v_mul_f32_e32 v244, 0xbfb8aa3b, v240
	v_mul_f32_e32 v245, 0xbfb8aa3b, v241
	v_mul_f32_e32 v246, 0xbfb8aa3b, v242
	v_mul_f32_e32 v247, 0xbfb8aa3b, v243
	v_exp_f32_e32 v244, v244
	v_exp_f32_e32 v245, v245
	v_exp_f32_e32 v246, v246
	v_exp_f32_e32 v247, v247
	v_pk_add_f32 v[244:245], v[244:245], v[252:253] op_sel_hi:[1,0]
	v_pk_add_f32 v[246:247], v[246:247], v[252:253] op_sel_hi:[1,0]
	v_rcp_f32_e32 v244, v244
	v_rcp_f32_e32 v245, v245
	v_rcp_f32_e32 v246, v246
	v_rcp_f32_e32 v247, v247
	v_mul_f32_e32 v240, v244, v240
	v_mul_f32_e32 v241, v245, v241
	v_mul_f32_e32 v242, v246, v242
	v_mul_f32_e32 v243, v247, v243
	v_mul_f32_e32 v240, v240, v4
	v_mul_f32_e32 v241, v241, v5
	v_mul_f32_e32 v242, v242, v6
	v_mul_f32_e32 v243, v243, v7
	v_cvt_pk_bf16_f32 v250, v240, v241
	v_cvt_pk_bf16_f32 v251, v242, v243
	s_nop 1
	v_permlane32_swap_b32_e32 v248, v250
	v_permlane32_swap_b32_e32 v249, v251
	global_store_dwordx4 v239, v[248:251], s[42:43]
	s_nop 1
	v_lshlrev_b32_e32 v240, 16, v191
	v_and_b32_e32 v241, 0xffff0000, v191
	v_lshlrev_b32_e32 v242, 16, v192
	v_and_b32_e32 v243, 0xffff0000, v192
	v_mul_f32_e32 v244, 0xbfb8aa3b, v240
	v_mul_f32_e32 v245, 0xbfb8aa3b, v241
	v_mul_f32_e32 v246, 0xbfb8aa3b, v242
	v_mul_f32_e32 v247, 0xbfb8aa3b, v243
	v_exp_f32_e32 v244, v244
	v_exp_f32_e32 v245, v245
	v_exp_f32_e32 v246, v246
	v_exp_f32_e32 v247, v247
	v_pk_add_f32 v[244:245], v[244:245], v[252:253] op_sel_hi:[1,0]
	v_pk_add_f32 v[246:247], v[246:247], v[252:253] op_sel_hi:[1,0]
	v_rcp_f32_e32 v244, v244
	v_rcp_f32_e32 v245, v245
	v_rcp_f32_e32 v246, v246
	v_rcp_f32_e32 v247, v247
	v_mul_f32_e32 v240, v244, v240
	v_mul_f32_e32 v241, v245, v241
	v_mul_f32_e32 v242, v246, v242
	v_mul_f32_e32 v243, v247, v243
	v_mul_f32_e32 v240, v240, v8
	v_mul_f32_e32 v241, v241, v9
	v_mul_f32_e32 v242, v242, v10
	v_mul_f32_e32 v243, v243, v11
	v_cvt_pk_bf16_f32 v248, v240, v241
	v_cvt_pk_bf16_f32 v249, v242, v243
	v_lshlrev_b32_e32 v240, 16, v193
	v_and_b32_e32 v241, 0xffff0000, v193
	v_lshlrev_b32_e32 v242, 16, v194
	v_and_b32_e32 v243, 0xffff0000, v194
	v_mul_f32_e32 v244, 0xbfb8aa3b, v240
	v_mul_f32_e32 v245, 0xbfb8aa3b, v241
	v_mul_f32_e32 v246, 0xbfb8aa3b, v242
	v_mul_f32_e32 v247, 0xbfb8aa3b, v243
	v_exp_f32_e32 v244, v244
	v_exp_f32_e32 v245, v245
	v_exp_f32_e32 v246, v246
	v_exp_f32_e32 v247, v247
	v_pk_add_f32 v[244:245], v[244:245], v[252:253] op_sel_hi:[1,0]
	v_pk_add_f32 v[246:247], v[246:247], v[252:253] op_sel_hi:[1,0]
	v_rcp_f32_e32 v244, v244
	v_rcp_f32_e32 v245, v245
	v_rcp_f32_e32 v246, v246
	v_rcp_f32_e32 v247, v247
	v_mul_f32_e32 v240, v244, v240
	v_mul_f32_e32 v241, v245, v241
	v_mul_f32_e32 v242, v246, v242
	v_mul_f32_e32 v243, v247, v243
	v_mul_f32_e32 v240, v240, v12
	v_mul_f32_e32 v241, v241, v13
	v_mul_f32_e32 v242, v242, v14
	v_mul_f32_e32 v243, v243, v15
	v_cvt_pk_bf16_f32 v250, v240, v241
	v_cvt_pk_bf16_f32 v251, v242, v243
	s_nop 1
	v_permlane32_swap_b32_e32 v248, v250
	v_permlane32_swap_b32_e32 v249, v251
	global_store_dwordx4 v239, v[248:251], s[42:43] offset:32
	s_nop 1
	v_lshlrev_b32_e32 v240, 16, v195
; __device__ __forceinline__ unsigned pk2(float lo, float hi) { f32x2_t v = {lo, hi}; bf16x2_t b = __builtin_convertvector(v, bf16x2_t); return __builtin_bit_cast(unsigned, b); }
; __device__ __forceinline__ float bflo(unsigned u) { return __uint_as_float(u << 16); }
; __device__ __forceinline__ float bfhi(unsigned u) { return __uint_as_float(u & 0xffff0000u); }
; __device__ __forceinline__ float sigmoid_(float x) { return rcpf_(1.0f + ex2(-LOG2E * x)); }
; __device__ __forceinline__ void attn_phase(const Ptrs& P, int gw, int NGW, int lane) {
;     ...
;             for (int g = 0; g < 4; g += 2) { v2u pk[2];
; #pragma unroll
;                 for (int e = 0; e < 2; ++e) { const v2u graw = gq_[dt * 4 + g + e]; const int i0 = 4 * (g + e);
;                     const float g0 = bflo(graw.x), g1 = bfhi(graw.x), g2 = bflo(graw.y), g3 = bfhi(graw.y);
;                     const float v0 = dt ? o1[i0] : o0[i0], v1 = dt ? o1[i0 + 1] : o0[i0 + 1], v2 = dt ? o1[i0 + 2] : o0[i0 + 2], v3 = dt ? o1[i0 + 3] : o0[i0 + 3];
;                     float w0 = v0 * (g0 * sigmoid_(g0)), w1 = v1 * (g1 * sigmoid_(g1)), w2 = v2 * (g2 * sigmoid_(g2)), w3 = v3 * (g3 * sigmoid_(g3));
;                     asm("" : "+v"(w0)); asm("" : "+v"(w1)); asm("" : "+v"(w2)); asm("" : "+v"(w3));
;                     pk[e].x = pk2(w0, w1); pk[e].y = pk2(w2, w3); }
;                 const auto rx = __builtin_amdgcn_permlane32_swap(pk[0].x, pk[1].x, false, false), ry = __builtin_amdgcn_permlane32_swap(pk[0].y, pk[1].y, false, false);
;                 const v4u o = {rx[0], ry[0], rx[1], ry[1]};
;                 *(v4u*)(op + dt * 32 + 8 * g) = o; }
	v_and_b32_e32 v241, 0xffff0000, v195
	v_lshlrev_b32_e32 v242, 16, v196
	v_and_b32_e32 v243, 0xffff0000, v196
	v_mul_f32_e32 v244, 0xbfb8aa3b, v240
	v_mul_f32_e32 v245, 0xbfb8aa3b, v241
	v_mul_f32_e32 v246, 0xbfb8aa3b, v242
	v_mul_f32_e32 v247, 0xbfb8aa3b, v243
	v_exp_f32_e32 v244, v244
	v_exp_f32_e32 v245, v245
	v_exp_f32_e32 v246, v246
	v_exp_f32_e32 v247, v247
	v_pk_add_f32 v[244:245], v[244:245], v[252:253] op_sel_hi:[1,0]
	v_pk_add_f32 v[246:247], v[246:247], v[252:253] op_sel_hi:[1,0]
	v_rcp_f32_e32 v244, v244
	v_rcp_f32_e32 v245, v245
	v_rcp_f32_e32 v246, v246
	v_rcp_f32_e32 v247, v247
	v_mul_f32_e32 v240, v244, v240
	v_mul_f32_e32 v241, v245, v241
	v_mul_f32_e32 v242, v246, v242
	v_mul_f32_e32 v243, v247, v243
	v_mul_f32_e32 v240, v240, v16
	v_mul_f32_e32 v241, v241, v17
	v_mul_f32_e32 v242, v242, v18
	v_mul_f32_e32 v243, v243, v19
	v_cvt_pk_bf16_f32 v248, v240, v241
	v_cvt_pk_bf16_f32 v249, v242, v243
	v_lshlrev_b32_e32 v240, 16, v197
	v_and_b32_e32 v241, 0xffff0000, v197
	v_lshlrev_b32_e32 v242, 16, v198
	v_and_b32_e32 v243, 0xffff0000, v198
	v_mul_f32_e32 v244, 0xbfb8aa3b, v240
	v_mul_f32_e32 v245, 0xbfb8aa3b, v241
	v_mul_f32_e32 v246, 0xbfb8aa3b, v242
	v_mul_f32_e32 v247, 0xbfb8aa3b, v243
	v_exp_f32_e32 v244, v244
	v_exp_f32_e32 v245, v245
	v_exp_f32_e32 v246, v246
	v_exp_f32_e32 v247, v247
	v_pk_add_f32 v[244:245], v[244:245], v[252:253] op_sel_hi:[1,0]
	v_pk_add_f32 v[246:247], v[246:247], v[252:253] op_sel_hi:[1,0]
	v_rcp_f32_e32 v244, v244
	v_rcp_f32_e32 v245, v245
	v_rcp_f32_e32 v246, v246
	v_rcp_f32_e32 v247, v247
	v_mul_f32_e32 v240, v244, v240
	v_mul_f32_e32 v241, v245, v241
	v_mul_f32_e32 v242, v246, v242
	v_mul_f32_e32 v243, v247, v243
	v_mul_f32_e32 v240, v240, v20
	v_mul_f32_e32 v241, v241, v21
	v_mul_f32_e32 v242, v242, v22
	v_mul_f32_e32 v243, v243, v23
	v_cvt_pk_bf16_f32 v250, v240, v241
	v_cvt_pk_bf16_f32 v251, v242, v243
	s_nop 1
	v_permlane32_swap_b32_e32 v248, v250
	v_permlane32_swap_b32_e32 v249, v251
	global_store_dwordx4 v239, v[248:251], s[42:43] offset:64
	s_nop 1
	v_lshlrev_b32_e32 v240, 16, v199
	v_and_b32_e32 v241, 0xffff0000, v199
	v_lshlrev_b32_e32 v242, 16, v200
	v_and_b32_e32 v243, 0xffff0000, v200
	v_mul_f32_e32 v244, 0xbfb8aa3b, v240
	v_mul_f32_e32 v245, 0xbfb8aa3b, v241
	v_mul_f32_e32 v246, 0xbfb8aa3b, v242
	v_mul_f32_e32 v247, 0xbfb8aa3b, v243
	v_exp_f32_e32 v244, v244
	v_exp_f32_e32 v245, v245
	v_exp_f32_e32 v246, v246
	v_exp_f32_e32 v247, v247
	v_pk_add_f32 v[244:245], v[244:245], v[252:253] op_sel_hi:[1,0]
	v_pk_add_f32 v[246:247], v[246:247], v[252:253] op_sel_hi:[1,0]
	v_rcp_f32_e32 v244, v244
	v_rcp_f32_e32 v245, v245
	v_rcp_f32_e32 v246, v246
	v_rcp_f32_e32 v247, v247
	v_mul_f32_e32 v240, v244, v240
	v_mul_f32_e32 v241, v245, v241
	v_mul_f32_e32 v242, v246, v242
	v_mul_f32_e32 v243, v247, v243
	v_mul_f32_e32 v240, v240, v24
	v_mul_f32_e32 v241, v241, v25
	v_mul_f32_e32 v242, v242, v26
	v_mul_f32_e32 v243, v243, v27
	v_cvt_pk_bf16_f32 v248, v240, v241
	v_cvt_pk_bf16_f32 v249, v242, v243
	v_lshlrev_b32_e32 v240, 16, v201
	v_and_b32_e32 v241, 0xffff0000, v201
	v_lshlrev_b32_e32 v242, 16, v202
	v_and_b32_e32 v243, 0xffff0000, v202
	v_mul_f32_e32 v244, 0xbfb8aa3b, v240
	v_mul_f32_e32 v245, 0xbfb8aa3b, v241
	v_mul_f32_e32 v246, 0xbfb8aa3b, v242
	v_mul_f32_e32 v247, 0xbfb8aa3b, v243
	v_exp_f32_e32 v244, v244
	v_exp_f32_e32 v245, v245
	v_exp_f32_e32 v246, v246
	v_exp_f32_e32 v247, v247
	v_pk_add_f32 v[244:245], v[244:245], v[252:253] op_sel_hi:[1,0]
	v_pk_add_f32 v[246:247], v[246:247], v[252:253] op_sel_hi:[1,0]
	v_rcp_f32_e32 v244, v244
	v_rcp_f32_e32 v245, v245
	v_rcp_f32_e32 v246, v246
	v_rcp_f32_e32 v247, v247
	v_mul_f32_e32 v240, v244, v240
	v_mul_f32_e32 v241, v245, v241
	v_mul_f32_e32 v242, v246, v242
	v_mul_f32_e32 v243, v247, v243
	v_mul_f32_e32 v240, v240, v28
	v_mul_f32_e32 v241, v241, v29
	v_mul_f32_e32 v242, v242, v30
	v_mul_f32_e32 v243, v243, v31
	v_cvt_pk_bf16_f32 v250, v240, v241
	v_cvt_pk_bf16_f32 v251, v242, v243
	s_nop 1
	v_permlane32_swap_b32_e32 v248, v250
	v_permlane32_swap_b32_e32 v249, v251
	global_store_dwordx4 v239, v[248:251], s[42:43] offset:96
	s_nop 1
	s_cmp_lg_u32 s82, 0
	s_cbranch_scc1 .Lp6_unit
